# P10-issue-epilogue-row-scale-and-conv-weight-loads-before-the-K-loop
# speedup vs baseline: 1.0194x; 1.0032x over previous
; #define GAS __attribute__((address_space(1)))
; #define LAS __attribute__((address_space(3)))
; __device__ __forceinline__ float row_rs(const float* SS, int row) {
;     const f32x4 a = *(const GAS f32x4*)(SS + (size_t)row * 16), b = *(const GAS f32x4*)(SS + (size_t)row * 16 + 4), c = *(const GAS f32x4*)(SS + (size_t)row * 16 + 8), d = *(const GAS f32x4*)(SS + (size_t)row * 16 + 12);
;     __device__ __forceinline__ void operator()(const pg8::f32x4 (&acc)[2][2][4][2], const pg8::Unit& u, int wr, int wc, int fr_, int fq_) const {
;     ...
;         for (int e = tid; e < 1024; e += 512) { const int k = e >> 8, cl = e & 255, gcol = (cl >> 7) * DFF + acol0 + (cl & 127); CW[e] = (k < 3) ? conv_w[k * UPW + gcol] : conv_b[gcol]; }
;         LAS float* RSL = BD + 2048;
;         if (tid < 256) RSL[tid] = row_rs(SS, u.pm * 256 + tid);
.LBB0_2574:
	v_readlane_b32 s8, v255, 28
	v_readlane_b32 s9, v255, 29
	v_lshl_add_u32 v228, s28, 8, v0
	v_ashrrev_i32_e32 v229, 31, v228
	v_lshlrev_b64 v[228:229], 6, v[228:229]
	v_cmp_gt_i32_e32 vcc, 0x100, v0
	v_lshl_add_u64 v[228:229], s[8:9], 0, v[228:229]
	s_and_saveexec_b64 s[10:11], vcc
	global_load_dwordx4 v[238:241], v[228:229], off offset:48
	global_load_dwordx4 v[242:245], v[228:229], off offset:32
	global_load_dwordx4 v[246:249], v[228:229], off offset:16
	global_load_dwordx4 v[250:253], v[228:229], off
	s_mov_b64 exec, s[10:11]
	v_readlane_b32 s10, v255, 1
	v_readlane_b32 s11, v255, 2
	s_lshl_b32 s12, s0, 7
	v_and_b32_e32 v229, 0x80, v0
	v_cmp_eq_u32_e32 vcc, 0, v229
	v_and_b32_e32 v228, 0x7f, v0
	v_lshrrev_b32_e32 v230, 8, v0
	v_or_b32_e32 v228, s12, v228
	v_cndmask_b32_e64 v229, v226, 0, vcc
	v_mul_u32_u24_e32 v230, 0x1600, v230
	v_add_u32_e32 v228, v228, v229
	v_cmp_gt_u32_e32 vcc, 0x100, v0
	v_add_u32_e32 v230, v228, v230
	v_mov_b32_e32 v231, 0
	v_mov_b32_e32 v234, s10
	v_lshl_add_u64 v[230:231], v[230:231], 2, s[10:11]
	v_mov_b32_e32 v235, s11
	global_load_dword v232, v[230:231], off
	v_mov_b32_e32 v230, s33
	v_mov_b32_e32 v231, s18
	v_mov_b32_e32 v236, 0x2c00
	v_mov_b32_e32 v229, 0
	v_cndmask_b32_e32 v230, v230, v234, vcc
	v_cndmask_b32_e32 v231, v231, v235, vcc
	v_cndmask_b32_e32 v236, 0, v236, vcc
	s_nop 0
	v_add_u32_e32 v228, v228, v236
	v_lshl_add_u64 v[228:229], v[228:229], 2, v[230:231]
	global_load_dword v233, v[228:229], off
	s_ashr_i32 s47, s46, 31
	s_lshl_b64 s[6:7], s[46:47], 19
	s_add_u32 s84, s38, s6
	s_addc_u32 s85, s39, s7
	s_ashr_i32 s45, s44, 31
	s_lshl_b64 s[6:7], s[44:45], 19
	s_add_u32 s88, s55, s6
	s_addc_u32 s89, s57, s7
	v_readlane_b32 s6, v255, 19
	v_readlane_b32 s7, v255, 20
	s_andn2_b64 vcc, exec, s[6:7]
	s_cbranch_vccz .Lmy_zr_7
	v_mov_b32_e32 v129, 0
	v_mov_b32_e32 v128, v129
	v_mov_b32_e32 v127, v129
	v_mov_b32_e32 v126, v129
	v_mov_b32_e32 v121, v129
	v_mov_b32_e32 v120, v129
	v_mov_b32_e32 v119, v129
	v_mov_b32_e32 v118, v129
	v_mov_b32_e32 v113, v129
	v_mov_b32_e32 v112, v129
	v_mov_b32_e32 v111, v129
	v_mov_b32_e32 v110, v129
	v_mov_b32_e32 v105, v129
	v_mov_b32_e32 v104, v129
	v_mov_b32_e32 v103, v129
	v_mov_b32_e32 v102, v129
	v_mov_b32_e32 v97, v129
	v_mov_b32_e32 v96, v129
	v_mov_b32_e32 v95, v129
	v_mov_b32_e32 v94, v129
	v_mov_b32_e32 v89, v129
	v_mov_b32_e32 v88, v129
	v_mov_b32_e32 v87, v129
	v_mov_b32_e32 v86, v129
	v_mov_b32_e32 v81, v129
	v_mov_b32_e32 v80, v129
	v_mov_b32_e32 v79, v129
	v_mov_b32_e32 v78, v129
	v_mov_b32_e32 v73, v129
	v_mov_b32_e32 v72, v129
	v_mov_b32_e32 v71, v129
	v_mov_b32_e32 v70, v129
	v_mov_b32_e32 v125, v129
	v_mov_b32_e32 v124, v129
	v_mov_b32_e32 v123, v129
	v_mov_b32_e32 v122, v129
	v_mov_b32_e32 v117, v129
	v_mov_b32_e32 v116, v129
	v_mov_b32_e32 v115, v129
	v_mov_b32_e32 v114, v129
	v_mov_b32_e32 v109, v129
	v_mov_b32_e32 v108, v129
	v_mov_b32_e32 v107, v129
	v_mov_b32_e32 v106, v129
	v_mov_b32_e32 v101, v129
	v_mov_b32_e32 v100, v129
	v_mov_b32_e32 v99, v129
	v_mov_b32_e32 v98, v129
	v_mov_b32_e32 v93, v129
	v_mov_b32_e32 v92, v129
	v_mov_b32_e32 v91, v129
	v_mov_b32_e32 v90, v129
	v_mov_b32_e32 v85, v129
	v_mov_b32_e32 v84, v129
	v_mov_b32_e32 v83, v129
	v_mov_b32_e32 v82, v129
	v_mov_b32_e32 v77, v129
	v_mov_b32_e32 v76, v129
	v_mov_b32_e32 v75, v129
	v_mov_b32_e32 v74, v129
	v_mov_b32_e32 v69, v129
	v_mov_b32_e32 v68, v129
	v_mov_b32_e32 v67, v129
	v_mov_b32_e32 v66, v129
	v_mov_b32_e32 v65, v129
	v_mov_b32_e32 v64, v129
	v_mov_b32_e32 v63, v129
	v_mov_b32_e32 v62, v129
	v_mov_b32_e32 v57, v129
	v_mov_b32_e32 v56, v129
	v_mov_b32_e32 v55, v129
	v_mov_b32_e32 v54, v129
	v_mov_b32_e32 v49, v129
	v_mov_b32_e32 v48, v129
	v_mov_b32_e32 v47, v129
	v_mov_b32_e32 v46, v129
	v_mov_b32_e32 v41, v129
	v_mov_b32_e32 v40, v129
	v_mov_b32_e32 v39, v129
	v_mov_b32_e32 v38, v129
	v_mov_b32_e32 v33, v129
	v_mov_b32_e32 v32, v129
	v_mov_b32_e32 v31, v129
	v_mov_b32_e32 v30, v129
	v_mov_b32_e32 v25, v129
	v_mov_b32_e32 v24, v129
	v_mov_b32_e32 v23, v129
	v_mov_b32_e32 v22, v129
	v_mov_b32_e32 v17, v129
	v_mov_b32_e32 v16, v129
	v_mov_b32_e32 v15, v129
	v_mov_b32_e32 v14, v129
	v_mov_b32_e32 v9, v129
	v_mov_b32_e32 v8, v129
	v_mov_b32_e32 v7, v129
	v_mov_b32_e32 v6, v129
	v_mov_b32_e32 v61, v129
	v_mov_b32_e32 v60, v129
	v_mov_b32_e32 v59, v129
	v_mov_b32_e32 v58, v129
	v_mov_b32_e32 v53, v129
	v_mov_b32_e32 v52, v129
	v_mov_b32_e32 v51, v129
	v_mov_b32_e32 v50, v129
	v_mov_b32_e32 v45, v129
	v_mov_b32_e32 v44, v129
	v_mov_b32_e32 v43, v129
	v_mov_b32_e32 v42, v129
	v_mov_b32_e32 v37, v129
	v_mov_b32_e32 v36, v129
	v_mov_b32_e32 v35, v129
	v_mov_b32_e32 v34, v129
	v_mov_b32_e32 v29, v129
	v_mov_b32_e32 v28, v129
	v_mov_b32_e32 v27, v129
	v_mov_b32_e32 v26, v129
	v_mov_b32_e32 v21, v129
	v_mov_b32_e32 v20, v129
	v_mov_b32_e32 v19, v129
	v_mov_b32_e32 v18, v129
	v_mov_b32_e32 v13, v129
	v_mov_b32_e32 v12, v129
	v_mov_b32_e32 v11, v129
	v_mov_b32_e32 v10, v129
	v_mov_b32_e32 v5, v129
	v_mov_b32_e32 v4, v129
	v_mov_b32_e32 v3, v129
	v_mov_b32_e32 v2, v129
	s_branch .LBB0_2577

;     __device__ __forceinline__ void operator()(const pg8::f32x4 (&acc)[2][2][4][2], const pg8::Unit& u, int wr, int wc, int fr_, int fq_) const {
;     ...
;         for (int e = tid; e < 1024; e += 512) { const int k = e >> 8, cl = e & 255, gcol = (cl >> 7) * DFF + acol0 + (cl & 127); CW[e] = (k < 3) ? conv_w[k * UPW + gcol] : conv_b[gcol]; }
.LBB0_2585:
	s_or_b64 exec, exec, s[6:7]
	v_and_b32_e32 v135, 2, v135
	v_cmp_eq_u32_e32 vcc, 0, v135
	s_and_saveexec_b64 s[6:7], vcc
	s_cbranch_execz .LBB0_2587
	v_readlane_b32 s60, v254, 63
	v_readlane_b32 s63, v255, 2
	v_readlane_b32 s62, v255, 1
	v_readlane_b32 s65, v255, 4
	v_readlane_b32 s64, v255, 3
	v_add_u32_e32 v135, v196, v136
	v_lshl_add_u32 v135, v135, 2, 0
	v_add_u32_e32 v135, 0x20000, v135
	v_readlane_b32 s61, v255, 0
	v_readlane_b32 s66, v255, 5
	v_readlane_b32 s67, v255, 6
	v_readlane_b32 s68, v255, 7
	v_readlane_b32 s69, v255, 8
	v_readlane_b32 s70, v255, 9
	v_readlane_b32 s71, v255, 10
	v_readlane_b32 s72, v255, 11
	v_readlane_b32 s73, v255, 12
	v_readlane_b32 s74, v255, 13
	v_readlane_b32 s75, v255, 14
	s_waitcnt vmcnt(0)
	ds_write2st64_b32 v135, v232, v233 offset1:8
